# residual-stream (X) row stores as plain stores instead of sc1 write-through
# baseline (speedup 1.0000x reference)
.LBB0_484:
	v_lshlrev_b64 v[138:139], 12, v[128:129]
	v_lshl_add_u64 v[138:139], v[104:105], 0, v[138:139]
	s_and_b64 vcc, exec, s[6:7]
	s_waitcnt vmcnt(3)
	global_store_dwordx4 v[138:139], v[94:97], off
	s_waitcnt vmcnt(3)
	global_store_dwordx4 v[138:139], v[90:93], off offset:1024
	s_waitcnt vmcnt(3)
	global_store_dwordx4 v[138:139], v[86:89], off offset:2048
	s_waitcnt vmcnt(3)
	global_store_dwordx4 v[138:139], v[82:85], off offset:3072
	s_cbranch_vccnz .LBB0_469
	v_mov_b32_e32 v138, v90
	v_mov_b32_e32 v139, v94
	v_pk_mul_f32 v[138:139], v[138:139], v[138:139]
	v_mov_b32_e32 v140, v91
	v_mov_b32_e32 v141, v95
	v_pk_fma_f32 v[138:139], v[140:141], v[140:141], v[138:139]
	v_mov_b32_e32 v140, v92
	v_mov_b32_e32 v141, v96
	v_pk_fma_f32 v[138:139], v[140:141], v[140:141], v[138:139]
	v_mov_b32_e32 v140, v93
	v_mov_b32_e32 v141, v97
	v_pk_fma_f32 v[138:139], v[140:141], v[140:141], v[138:139]
	v_mov_b32_e32 v140, v82
	v_mov_b32_e32 v141, v86
	v_pk_mul_f32 v[140:141], v[140:141], v[140:141]
	v_mov_b32_e32 v142, v83
	v_mov_b32_e32 v143, v87
	v_pk_fma_f32 v[140:141], v[142:143], v[142:143], v[140:141]
	v_mov_b32_e32 v142, v84
	v_mov_b32_e32 v143, v88
	v_pk_fma_f32 v[140:141], v[142:143], v[142:143], v[140:141]
	v_mov_b32_e32 v142, v85
	v_mov_b32_e32 v143, v89
	v_add_u32_e32 v137, 64, v137
	v_pk_fma_f32 v[140:141], v[142:143], v[142:143], v[140:141]
	v_add_f32_e32 v138, v138, v139
	v_cmp_lt_i32_e32 vcc, v136, v137
	v_add_f32_e32 v138, v141, v138
	v_add_f32_e32 v138, v140, v138
	v_lshlrev_b64 v[128:129], 11, v[128:129]
	v_lshl_add_u64 v[128:129], v[106:107], 0, v[128:129]
	s_nop 1
	v_add_f32_dpp v138, v138, v138 quad_perm:[1,0,3,2] row_mask:0xf bank_mask:0xf
	s_nop 1
	v_add_f32_dpp v138, v138, v138 quad_perm:[2,3,0,1] row_mask:0xf bank_mask:0xf
	s_nop 1
	v_add_f32_dpp v138, v138, v138 row_half_mirror row_mask:0xf bank_mask:0xf
	s_nop 1
	v_add_f32_dpp v138, v138, v138 row_mirror row_mask:0xf bank_mask:0xf
	v_mov_b32_e32 v140, v138
	s_nop 1
	v_permlane16_swap_b32 v138, v140
	v_add_f32_e32 v138, v138, v140
	v_mov_b32_e32 v140, v138
	s_nop 1
	v_permlane32_swap_b32 v138, v140
	v_add_f32_e32 v138, v138, v140
	v_mov_b32_e32 v130, v138
	v_fmamk_f32 v130, v130, 0x3a800000, v197
	v_mul_f32_e32 v132, 0x4b800000, v130
	v_cmp_gt_f32_e32 vcc, s14, v130
	s_nop 1
	v_cndmask_b32_e32 v130, v130, v132, vcc
	v_rsq_f32_e32 v130, v130
	s_nop 0
	v_mul_f32_e32 v132, 0x45800000, v130
	v_cndmask_b32_e32 v130, v130, v132, vcc
	v_pk_mul_f32 v[94:95], v[94:95], v[130:131] op_sel_hi:[1,0]
	v_pk_add_f32 v[132:133], v[6:7], 1.0 op_sel_hi:[1,0]
	v_pk_mul_f32 v[94:95], v[2:3], v[94:95]
	v_pk_mul_f32 v[96:97], v[96:97], v[130:131] op_sel_hi:[1,0]
	v_pk_fma_f32 v[94:95], v[132:133], v[94:95], v[14:15]
	v_pk_add_f32 v[132:133], v[8:9], 1.0 op_sel_hi:[1,0]
	v_pk_mul_f32 v[96:97], v[4:5], v[96:97]
	v_cvt_pk_bf16_f32 v94, v94, v95
	v_pk_fma_f32 v[96:97], v[132:133], v[96:97], v[16:17]
	v_pk_mul_f32 v[90:91], v[90:91], v[130:131] op_sel_hi:[1,0]
	v_cvt_pk_bf16_f32 v95, v96, v97
	global_store_dwordx2 v[128:129], v[94:95], off
	v_pk_add_f32 v[94:95], v[22:23], 1.0 op_sel_hi:[1,0]
	v_pk_mul_f32 v[90:91], v[18:19], v[90:91]
	v_pk_mul_f32 v[92:93], v[92:93], v[130:131] op_sel_hi:[1,0]
	v_pk_fma_f32 v[90:91], v[94:95], v[90:91], v[30:31]
	v_pk_add_f32 v[94:95], v[24:25], 1.0 op_sel_hi:[1,0]
	v_pk_mul_f32 v[92:93], v[20:21], v[92:93]
	v_cvt_pk_bf16_f32 v90, v90, v91
	v_pk_fma_f32 v[92:93], v[94:95], v[92:93], v[32:33]
	v_pk_mul_f32 v[86:87], v[86:87], v[130:131] op_sel_hi:[1,0]
	v_cvt_pk_bf16_f32 v91, v92, v93
	global_store_dwordx2 v[128:129], v[90:91], off offset:512
	v_pk_add_f32 v[90:91], v[46:47], 1.0 op_sel_hi:[1,0]
	v_pk_mul_f32 v[86:87], v[34:35], v[86:87]
	v_pk_mul_f32 v[88:89], v[88:89], v[130:131] op_sel_hi:[1,0]
	v_pk_fma_f32 v[86:87], v[90:91], v[86:87], v[50:51]
	v_pk_add_f32 v[90:91], v[48:49], 1.0 op_sel_hi:[1,0]
	v_pk_mul_f32 v[88:89], v[36:37], v[88:89]
	v_cvt_pk_bf16_f32 v86, v86, v87
	v_pk_fma_f32 v[88:89], v[90:91], v[88:89], v[52:53]
	v_pk_mul_f32 v[82:83], v[82:83], v[130:131] op_sel_hi:[1,0]
	v_cvt_pk_bf16_f32 v87, v88, v89
	global_store_dwordx2 v[128:129], v[86:87], off offset:1024
	v_pk_add_f32 v[86:87], v[62:63], 1.0 op_sel_hi:[1,0]
	v_pk_mul_f32 v[82:83], v[58:59], v[82:83]
	v_pk_mul_f32 v[84:85], v[84:85], v[130:131] op_sel_hi:[1,0]
	v_pk_fma_f32 v[82:83], v[86:87], v[82:83], v[70:71]
	v_pk_add_f32 v[86:87], v[64:65], 1.0 op_sel_hi:[1,0]
	v_pk_mul_f32 v[84:85], v[60:61], v[84:85]
	v_cvt_pk_bf16_f32 v82, v82, v83
	v_pk_fma_f32 v[84:85], v[86:87], v[84:85], v[72:73]
	s_nop 0
	v_cvt_pk_bf16_f32 v83, v84, v85
	global_store_dwordx2 v[128:129], v[82:83], off offset:1536
	s_branch .LBB0_469
